# attention prompt q-loop: waves 4-7 enter the loop s_sleep 20 later (half-block stagger of the SIMD partners)
# speedup vs baseline: 1.0033x; 1.0002x over previous
.LBB0_618:
	s_or_b64 exec, exec, s[22:23]
	s_ashr_i32 s8, s54, 6
	s_add_i32 s10, s8, s25
	s_ashr_i32 s11, s10, 31
	s_and_b32 s12, s28, 63
	s_lshl_b64 s[10:11], s[10:11], 2
	s_add_u32 s10, s76, s10
	s_addc_u32 s11, s77, s11
	s_waitcnt lgkmcnt(0)
	s_barrier
	global_load_dword v0, v3, s[10:11]
	v_and_b32_e32 v8, 15, v137
	v_or_b32_e32 v63, s3, v8
	s_ashr_i32 s3, s2, 31
	s_lshl_b64 s[10:11], s[2:3], 13
	v_or_b32_e32 v2, s10, v63
	v_bfe_u32 v9, v137, 4, 2
	v_readlane_b32 s60, v254, 51
	v_readlane_b32 s61, v254, 52
	v_lshlrev_b32_e32 v6, 5, v9
	v_mov_b32_e32 v7, v3
	s_mov_b64 s[22:23], s[90:91]
	v_lshlrev_b32_e32 v10, 3, v9
	s_mov_b32 s3, 16
	s_mov_b32 s8, 0
	v_lshl_add_u64 v[52:53], s[88:89], 0, v[6:7]
	s_mov_b64 s[18:19], s[22:23]
	v_lshl_add_u64 v[54:55], s[22:23], 0, v[6:7]
	v_lshl_add_u64 v[56:57], s[60:61], 0, v[6:7]
	s_mov_b32 s22, 0
	s_waitcnt vmcnt(0)
	v_mul_f32_e32 v62, 0x3fb8aa3b, v0
	v_mov_b64_e32 v[0:1], s[94:95]
	v_mad_u64_u32 v[0:1], s[14:15], v2, s34, v[0:1]
	s_and_b32 s14, s54, 0xffffffc0
	v_mov_b32_e32 v2, 0x1a00
	s_ashr_i32 s15, s14, 31
	v_mad_i32_i24 v1, s11, v2, v1
	s_lshl_b64 s[52:53], s[14:15], 1
	v_lshl_add_u64 v[0:1], v[0:1], 0, s[52:53]
	v_lshlrev_b32_e32 v2, 4, v9
	v_lshl_add_u64 v[0:1], v[0:1], 0, v[2:3]
	global_load_dwordx4 v[32:35], v[0:1], off
	global_load_dwordx4 v[28:31], v[0:1], off offset:64
	v_lshlrev_b32_e32 v0, 7, v63
	v_mov_b32_e32 v1, v3
	v_lshl_add_u64 v[4:5], s[90:91], 0, v[0:1]
	v_lshl_add_u64 v[0:1], s[60:61], 0, v[0:1]
	v_lshl_add_u64 v[4:5], v[4:5], 0, v[6:7]
	v_lshl_add_u64 v[0:1], v[0:1], 0, v[6:7]
	global_load_dwordx4 v[36:39], v[4:5], off offset:16
	global_load_dwordx4 v[40:43], v[4:5], off
	global_load_dwordx4 v[44:47], v[0:1], off offset:16
	global_load_dwordx4 v[48:51], v[0:1], off
	v_xor_b32_e32 v0, 16, v146
	v_cmp_lt_i32_e32 vcc, v0, v147
	s_cmp_lg_u32 s57, 0
	s_cselect_b64 s[90:91], -1, 0
	v_cndmask_b32_e32 v0, v146, v0, vcc
	v_lshlrev_b32_e32 v64, 2, v0
	v_xor_b32_e32 v0, 32, v146
	v_cmp_lt_i32_e32 vcc, v0, v147
	s_nop 1
	v_cndmask_b32_e32 v0, v146, v0, vcc
	v_lshlrev_b32_e32 v65, 2, v0
	v_lshlrev_b32_e32 v0, 2, v9
	v_or_b32_e32 v1, 2, v0
	v_cmp_gt_u32_e64 s[42:43], v1, v8
	v_or_b32_e32 v1, 3, v0
	v_cmp_gt_u32_e32 vcc, v0, v8
	v_cmp_ge_u32_e64 s[40:41], v0, v8
	v_cmp_gt_u32_e64 s[46:47], v1, v8
	s_and_b64 s[38:39], s[90:91], vcc
	s_and_b64 s[40:41], s[90:91], s[40:41]
	s_and_b64 s[44:45], s[90:91], s[42:43]
	s_and_b64 s[48:49], s[90:91], s[46:47]
	s_add_u32 s14, s94, s52
	s_addc_u32 s15, s95, s53
	s_lshr_b32 s13, s54, 8
	v_lshl_add_u64 v[58:59], s[14:15], 0, v[2:3]
	s_mul_i32 s14, s13, 0x8400
	v_cmp_lt_u32_e64 s[50:51], v0, v8
	v_mov_b32_e32 v0, s14
	s_movk_i32 s14, 0x210
	v_mad_u32_u24 v0, v8, s14, v0
	v_lshl_or_b32 v1, s12, 7, v8
	v_add3_u32 v66, v0, v10, 0
	s_mul_i32 s13, s13, 0x9000
	v_mul_u32_u24_e32 v0, 0x90, v8
	v_mul_hi_u32_u24_e32 v5, 0xc00, v1
	v_mul_u32_u24_e32 v4, 0xc00, v1
	v_mov_b32_e32 v1, 0x1800000
	v_or_b32_e32 v0, s13, v0
	v_mad_i64_i32 v[4:5], s[12:13], s2, v1, v[4:5]
	s_add_u32 s12, s26, s52
	v_or_b32_e32 v4, v4, v10
	s_addc_u32 s13, s27, s53
	v_add3_u32 v0, v0, v2, 0
	v_lshl_add_u64 v[60:61], s[12:13], 0, v[4:5]
	v_readfirstlane_b32 s100, v207
	s_bitcmp1_b32 s100, 8
	s_cbranch_scc0 .Lstag_attn
	s_sleep 20
.Lstag_attn:
.LBB0_619:
	s_add_i32 s2, s22, 1
	s_cmpk_lg_i32 s8, 0xe0
	s_cselect_b32 s12, s3, 0x70
	v_add_u32_e32 v2, s12, v63
	v_lshl_add_u64 v[4:5], s[10:11], 0, v[2:3]
	v_mad_u64_u32 v[6:7], s[12:13], v4, s34, v[58:59]
	v_lshlrev_b64 v[8:9], 7, v[2:3]
	s_waitcnt vmcnt(4)
	v_lshlrev_b32_e32 v86, 16, v31
	v_and_b32_e32 v87, 0xffff0000, v31
	v_mad_i32_i24 v7, v5, s34, v7
	v_lshl_add_u64 v[10:11], v[54:55], 0, v[8:9]
	v_lshl_add_u64 v[12:13], v[56:57], 0, v[8:9]
	v_lshlrev_b32_e32 v84, 16, v35
	v_and_b32_e32 v85, 0xffff0000, v35
	v_pk_mul_f32 v[68:69], v[86:87], v[86:87]
	v_pk_fma_f32 v[88:89], v[84:85], v[84:85], v[68:69]
	s_nop 0
	global_load_dwordx4 v[68:71], v[52:53], off offset:16
	global_load_dwordx4 v[72:75], v[52:53], off
	global_load_dwordx4 v[76:79], v[52:53], off offset:144
	global_load_dwordx4 v[80:83], v[52:53], off offset:128
	global_load_dwordx4 v[20:23], v[6:7], off
	global_load_dwordx4 v[24:27], v[6:7], off offset:64
	s_nop 0
	global_load_dwordx4 v[4:7], v[10:11], off offset:16
	global_load_dwordx4 v[16:19], v[10:11], off
	s_nop 0
	global_load_dwordx4 v[8:11], v[12:13], off offset:16
	s_nop 0
	global_load_dwordx4 v[12:15], v[12:13], off
	v_lshlrev_b32_e32 v92, 16, v33
	v_and_b32_e32 v93, 0xffff0000, v33
	v_lshlrev_b32_e32 v98, 16, v32
	v_and_b32_e32 v99, 0xffff0000, v32
	v_lshlrev_b32_e32 v32, 16, v28
	v_and_b32_e32 v33, 0xffff0000, v28
	v_lshlrev_b32_e32 v94, 16, v29
	v_and_b32_e32 v95, 0xffff0000, v29
	v_pk_mul_f32 v[28:29], v[32:33], v[32:33]
	v_pk_mul_f32 v[96:97], v[94:95], v[94:95]
	v_pk_fma_f32 v[28:29], v[98:99], v[98:99], v[28:29]
	v_lshlrev_b32_e32 v90, 16, v34
	v_and_b32_e32 v91, 0xffff0000, v34
	v_lshlrev_b32_e32 v34, 16, v30
	v_and_b32_e32 v35, 0xffff0000, v30
	v_pk_fma_f32 v[96:97], v[92:93], v[92:93], v[96:97]
	v_add_f32_e32 v1, v28, v29
	v_pk_mul_f32 v[30:31], v[34:35], v[34:35]
	v_add_f32_e32 v1, v96, v1
	v_pk_fma_f32 v[30:31], v[90:91], v[90:91], v[30:31]
	v_add_f32_e32 v1, v97, v1
	v_add_f32_e32 v1, v30, v1
	v_add_f32_e32 v1, v31, v1
	v_add_f32_e32 v1, v88, v1
	v_add_f32_e32 v1, v89, v1
	ds_bpermute_b32 v2, v64, v1
	s_mov_b32 s12, 0xff800000
	s_cmp_gt_u32 s22, 6
	s_waitcnt lgkmcnt(0)
	v_add_f32_e32 v1, v1, v2
	ds_bpermute_b32 v2, v65, v1
	s_waitcnt lgkmcnt(0)
	v_add_f32_e32 v1, v1, v2
	v_fmamk_f32 v1, v1, 0x3c800000, v191
	v_cmp_gt_f32_e64 s[54:55], s71, v1
	v_mul_f32_e32 v2, 0x4b800000, v1
	s_nop 0
	v_cndmask_b32_e64 v1, v1, v2, s[54:55]
	v_rsq_f32_e32 v1, v1
	s_nop 0
	v_mul_f32_e32 v2, 0x45800000, v1
	v_cndmask_b32_e64 v1, v1, v2, s[54:55]
	v_mul_f32_e32 v2, 0x3e38aa3b, v1
	v_pk_mul_f32 v[30:31], v[2:3], v[32:33] op_sel_hi:[0,1]
	v_pk_mul_f32 v[28:29], v[2:3], v[98:99] op_sel_hi:[0,1]
	v_pk_mul_f32 v[34:35], v[2:3], v[34:35] op_sel_hi:[0,1]
	s_waitcnt vmcnt(8)
	v_pk_mul_f32 v[28:29], v[72:73], v[28:29]
	s_waitcnt vmcnt(7)
	v_pk_mul_f32 v[34:35], v[76:77], v[34:35]
	s_waitcnt vmcnt(6)
	v_pk_mul_f32 v[30:31], v[80:81], v[30:31]
	s_nop 0
	v_pk_mul_f32 v[32:33], v[48:49], v[30:31]
	s_nop 0
	v_pk_fma_f32 v[32:33], v[40:41], v[28:29], v[32:33] neg_lo:[0,0,1] neg_hi:[0,0,1]
	v_pk_mul_f32 v[28:29], v[48:49], v[28:29]
	v_cvt_pk_bf16_f32 v32, v32, v33
	v_pk_fma_f32 v[28:29], v[40:41], v[30:31], v[28:29]
	v_pk_mul_f32 v[40:41], v[2:3], v[94:95] op_sel_hi:[0,1]
	v_pk_mul_f32 v[30:31], v[2:3], v[92:93] op_sel_hi:[0,1]
	v_pk_mul_f32 v[40:41], v[82:83], v[40:41]
	v_pk_mul_f32 v[30:31], v[74:75], v[30:31]
	v_pk_mul_f32 v[48:49], v[50:51], v[40:41]
	v_cvt_pk_bf16_f32 v28, v28, v29
	v_pk_fma_f32 v[48:49], v[42:43], v[30:31], v[48:49] neg_lo:[0,0,1] neg_hi:[0,0,1]
	v_pk_mul_f32 v[30:31], v[50:51], v[30:31]
	v_cvt_pk_bf16_f32 v33, v48, v49
	v_pk_fma_f32 v[30:31], v[42:43], v[40:41], v[30:31]
	v_pk_mul_f32 v[40:41], v[2:3], v[90:91] op_sel_hi:[0,1]
	v_pk_mul_f32 v[40:41], v[68:69], v[40:41]
	v_pk_mul_f32 v[42:43], v[44:45], v[34:35]
	v_pk_mul_f32 v[34:35], v[36:37], v[34:35]
	v_pk_fma_f32 v[42:43], v[36:37], v[40:41], v[42:43] neg_lo:[0,0,1] neg_hi:[0,0,1]
	v_pk_fma_f32 v[36:37], v[44:45], v[40:41], v[34:35]
	v_pk_mul_f32 v[40:41], v[2:3], v[86:87] op_sel_hi:[0,1]
	v_pk_mul_f32 v[34:35], v[2:3], v[84:85] op_sel_hi:[0,1]
	v_pk_mul_f32 v[40:41], v[40:41], v[78:79]
	v_pk_mul_f32 v[34:35], v[34:35], v[70:71]
	v_pk_mul_f32 v[44:45], v[46:47], v[40:41]
	v_cvt_pk_bf16_f32 v29, v30, v31
	v_pk_fma_f32 v[44:45], v[38:39], v[34:35], v[44:45] neg_lo:[0,0,1] neg_hi:[0,0,1]
	v_pk_mul_f32 v[38:39], v[38:39], v[40:41]
	v_cvt_pk_bf16_f32 v30, v36, v37
	v_pk_fma_f32 v[38:39], v[46:47], v[34:35], v[38:39]
	v_cvt_pk_bf16_f32 v34, v42, v43
	v_cvt_pk_bf16_f32 v31, v38, v39
	ds_read_b128 v[36:39], v0
	ds_read_b128 v[40:43], v0 offset:64
	v_cvt_pk_bf16_f32 v35, v44, v45
	s_waitcnt lgkmcnt(1)
	s_nop 0
	v_mfma_f32_16x16x32_bf16 v[36:39], v[36:39], v[32:35], 0
	s_waitcnt lgkmcnt(0)
	v_mfma_f32_16x16x32_bf16 v[36:39], v[40:43], v[28:31], v[36:39]
	ds_read_b128 v[42:45], v0 offset:2368
	s_nop 6
	v_cndmask_b32_e64 v2, v204, v37, s[40:41]
	v_cndmask_b32_e64 v37, v204, v38, s[44:45]
	v_cndmask_b32_e64 v46, v204, v39, s[48:49]
	ds_read_b128 v[38:41], v0 offset:2304
	s_waitcnt lgkmcnt(0)
	v_mfma_f32_16x16x32_bf16 v[38:41], v[38:41], v[32:35], 0
	v_cndmask_b32_e64 v1, v204, v36, s[38:39]
	v_max3_f32 v36, v1, s12, v2
	s_cselect_b64 s[12:13], -1, 0
	v_mfma_f32_16x16x32_bf16 v[38:41], v[42:45], v[28:31], v[38:41]
	s_or_b64 s[54:55], s[90:91], s[12:13]
	v_max3_f32 v47, v36, v37, v46
	ds_read_b128 v[42:45], v0 offset:4672
	s_cmp_gt_u32 s22, 5
	s_cselect_b64 s[12:13], -1, 0
	s_nop 2
	v_cndmask_b32_e64 v48, v204, v38, s[54:55]
	v_cndmask_b32_e64 v49, v204, v39, s[54:55]
	v_max3_f32 v38, v47, v48, v49
	v_cndmask_b32_e64 v47, v204, v40, s[54:55]
	v_cndmask_b32_e64 v50, v204, v41, s[54:55]
	v_max3_f32 v51, v38, v47, v50
	ds_read_b128 v[38:41], v0 offset:4608
	s_waitcnt lgkmcnt(0)
	v_mfma_f32_16x16x32_bf16 v[38:41], v[38:41], v[32:35], 0
	s_or_b64 s[54:55], s[90:91], s[12:13]
	s_cmp_gt_u32 s22, 4
	s_cselect_b64 s[12:13], -1, 0
	v_mfma_f32_16x16x32_bf16 v[38:41], v[42:45], v[28:31], v[38:41]
	ds_read_b128 v[42:45], v0 offset:6976
	v_add_u32_e32 v36, 0x900, v0
	s_nop 5
	v_cndmask_b32_e64 v67, v204, v38, s[54:55]
	v_cndmask_b32_e64 v68, v204, v39, s[54:55]
	v_max3_f32 v38, v51, v67, v68
	v_cndmask_b32_e64 v51, v204, v40, s[54:55]
	v_cndmask_b32_e64 v69, v204, v41, s[54:55]
	v_max3_f32 v70, v38, v51, v69
	ds_read_b128 v[38:41], v0 offset:6912
	s_waitcnt lgkmcnt(0)
	v_mfma_f32_16x16x32_bf16 v[38:41], v[38:41], v[32:35], 0
	s_or_b64 s[54:55], s[90:91], s[12:13]
	s_cmp_gt_u32 s22, 3
	s_cselect_b64 s[12:13], -1, 0
	v_mfma_f32_16x16x32_bf16 v[38:41], v[42:45], v[28:31], v[38:41]
	ds_read_b128 v[42:45], v0 offset:9280
	s_nop 6
	v_cndmask_b32_e64 v71, v204, v38, s[54:55]
	v_cndmask_b32_e64 v72, v204, v39, s[54:55]
	v_max3_f32 v38, v70, v71, v72
	v_cndmask_b32_e64 v70, v204, v40, s[54:55]
	v_cndmask_b32_e64 v73, v204, v41, s[54:55]
	v_max3_f32 v74, v38, v70, v73
	ds_read_b128 v[38:41], v0 offset:9216
	s_waitcnt lgkmcnt(0)
	v_mfma_f32_16x16x32_bf16 v[38:41], v[38:41], v[32:35], 0
	s_or_b64 s[54:55], s[90:91], s[12:13]
	s_cmp_gt_u32 s22, 2
	s_cselect_b64 s[12:13], -1, 0
	v_mfma_f32_16x16x32_bf16 v[38:41], v[42:45], v[28:31], v[38:41]
	ds_read_b128 v[42:45], v0 offset:11584
	s_nop 6
	v_cndmask_b32_e64 v75, v204, v38, s[54:55]
	v_cndmask_b32_e64 v76, v204, v39, s[54:55]
	v_max3_f32 v38, v74, v75, v76
	v_cndmask_b32_e64 v74, v204, v40, s[54:55]
	v_cndmask_b32_e64 v77, v204, v41, s[54:55]
	v_max3_f32 v78, v38, v74, v77
	ds_read_b128 v[38:41], v0 offset:11520
	s_waitcnt lgkmcnt(0)
	v_mfma_f32_16x16x32_bf16 v[38:41], v[38:41], v[32:35], 0
	s_or_b64 s[54:55], s[90:91], s[12:13]
	s_cmp_gt_u32 s22, 1
	s_cselect_b64 s[12:13], -1, 0
	v_mfma_f32_16x16x32_bf16 v[38:41], v[42:45], v[28:31], v[38:41]
	ds_read_b128 v[42:45], v0 offset:13888
	s_nop 6
	v_cndmask_b32_e64 v79, v204, v38, s[54:55]
	v_cndmask_b32_e64 v80, v204, v39, s[54:55]
	v_max3_f32 v38, v78, v79, v80
	v_cndmask_b32_e64 v78, v204, v40, s[54:55]
	v_cndmask_b32_e64 v81, v204, v41, s[54:55]
	v_max3_f32 v82, v38, v78, v81
	ds_read_b128 v[38:41], v0 offset:13824
	s_waitcnt lgkmcnt(0)
	v_mfma_f32_16x16x32_bf16 v[38:41], v[38:41], v[32:35], 0
	s_or_b64 s[54:55], s[90:91], s[12:13]
	s_or_b32 s12, s22, s57
	s_cmp_eq_u32 s12, 0
	v_mfma_f32_16x16x32_bf16 v[38:41], v[42:45], v[28:31], v[38:41]
	ds_read_b128 v[42:45], v0 offset:16192
	s_mov_b64 s[12:13], 0xc000
	s_mov_b32 s22, s2
	s_nop 4
	v_cndmask_b32_e64 v83, v204, v38, s[54:55]
	v_cndmask_b32_e64 v84, v204, v39, s[54:55]
	v_max3_f32 v38, v82, v83, v84
	v_cndmask_b32_e64 v82, v204, v40, s[54:55]
	v_cndmask_b32_e64 v85, v204, v41, s[54:55]
	v_max3_f32 v86, v38, v82, v85
	ds_read_b128 v[38:41], v0 offset:16128
	s_waitcnt lgkmcnt(0)
	v_mfma_f32_16x16x32_bf16 v[38:41], v[38:41], v[32:35], 0
	s_cselect_b64 s[54:55], -1, 0
	s_add_i32 s3, s3, 16
	v_mfma_f32_16x16x32_bf16 v[38:41], v[42:45], v[28:31], v[38:41]
	s_nop 7
	v_cndmask_b32_e64 v42, v38, v204, s[54:55]
	v_cndmask_b32_e64 v87, v39, v204, s[54:55]
	v_max3_f32 v38, v86, v42, v87
	v_cndmask_b32_e64 v86, v40, v204, s[54:55]
	v_cndmask_b32_e64 v88, v41, v204, s[54:55]
	v_max3_f32 v43, v38, v86, v88
	ds_read_b128 v[38:41], v0 offset:18432
	s_waitcnt lgkmcnt(0)
	v_mfma_f32_16x16x32_bf16 v[32:35], v[38:41], v[32:35], 0
	ds_read_b128 v[38:41], v0 offset:18496
	s_waitcnt lgkmcnt(0)
	v_mfma_f32_16x16x32_bf16 v[28:31], v[38:41], v[28:31], v[32:35]
	s_nop 7
	v_cndmask_b32_e32 v28, v28, v204, vcc
	v_cndmask_b32_e64 v29, v204, v29, s[50:51]
	v_max3_f32 v0, v43, v28, v29
	v_cndmask_b32_e64 v30, v30, v204, s[42:43]
	v_cndmask_b32_e64 v31, v31, v204, s[46:47]
	v_max3_f32 v0, v0, v30, v31
	ds_bpermute_b32 v32, v64, v0
	s_waitcnt lgkmcnt(0)
	v_max_f32_e32 v32, v32, v32
	v_max_f32_e32 v0, v0, v32
	ds_bpermute_b32 v32, v65, v0
	s_waitcnt lgkmcnt(0)
	v_max3_f32 v32, v0, v32, v62
	v_sub_f32_e32 v0, v1, v32
	v_exp_f32_e32 v89, v0
	v_sub_f32_e32 v1, v2, v32
	v_exp_f32_e32 v90, v1
	v_sub_f32_e32 v1, v37, v32
	v_exp_f32_e32 v91, v1
	v_sub_f32_e32 v1, v46, v32
	v_exp_f32_e32 v92, v1
	v_sub_f32_e32 v1, v48, v32
	v_add_f32_e32 v0, 0, v89
	v_exp_f32_e32 v93, v1
	v_sub_f32_e32 v1, v49, v32
	v_add_f32_e32 v0, v90, v0
	v_exp_f32_e32 v94, v1
	v_sub_f32_e32 v1, v47, v32
	v_add_f32_e32 v0, v91, v0
	v_exp_f32_e32 v95, v1
	v_sub_f32_e32 v1, v50, v32
	v_add_f32_e32 v0, v92, v0
	v_exp_f32_e32 v96, v1
	v_add_f32_e32 v0, v93, v0
	v_add_f32_e32 v0, v94, v0
	v_add_f32_e32 v0, v95, v0
	v_add_f32_e32 v1, v96, v0
	v_sub_f32_e32 v0, v67, v32
	v_exp_f32_e32 v0, v0
	v_sub_f32_e32 v2, v68, v32
	v_exp_f32_e32 v34, v2
	v_sub_f32_e32 v2, v51, v32
	v_exp_f32_e32 v39, v2
	v_sub_f32_e32 v2, v69, v32
	v_exp_f32_e32 v43, v2
	v_sub_f32_e32 v2, v71, v32
	v_add_f32_e32 v1, v0, v1
	v_exp_f32_e32 v47, v2
	v_sub_f32_e32 v2, v72, v32
	v_add_f32_e32 v1, v34, v1
	v_exp_f32_e32 v50, v2
	v_sub_f32_e32 v2, v70, v32
	v_add_f32_e32 v1, v39, v1
	v_exp_f32_e32 v68, v2
	v_sub_f32_e32 v2, v73, v32
	v_add_f32_e32 v1, v43, v1
	v_exp_f32_e32 v71, v2
	v_add_f32_e32 v1, v47, v1
	v_add_f32_e32 v1, v50, v1
	v_add_f32_e32 v1, v68, v1
	v_add_f32_e32 v2, v71, v1
	v_sub_f32_e32 v1, v75, v32
	v_exp_f32_e32 v1, v1
	v_sub_f32_e32 v33, v76, v32
	v_exp_f32_e32 v35, v33
	v_sub_f32_e32 v33, v74, v32
	v_exp_f32_e32 v40, v33
	v_sub_f32_e32 v33, v77, v32
	v_exp_f32_e32 v44, v33
	v_sub_f32_e32 v33, v79, v32
	v_add_f32_e32 v2, v1, v2
	v_exp_f32_e32 v48, v33
	v_sub_f32_e32 v33, v80, v32
	v_add_f32_e32 v2, v35, v2
	v_exp_f32_e32 v51, v33
	v_sub_f32_e32 v33, v78, v32
	v_add_f32_e32 v2, v40, v2
	v_exp_f32_e32 v69, v33
	v_sub_f32_e32 v33, v81, v32
	v_add_f32_e32 v2, v44, v2
	v_exp_f32_e32 v72, v33
	v_add_f32_e32 v2, v48, v2
	v_add_f32_e32 v2, v51, v2
	v_add_f32_e32 v2, v69, v2
	v_add_f32_e32 v33, v72, v2
	v_sub_f32_e32 v2, v83, v32
	v_exp_f32_e32 v2, v2
	v_sub_f32_e32 v37, v84, v32
	v_exp_f32_e32 v37, v37
	v_sub_f32_e32 v38, v82, v32
	v_exp_f32_e32 v41, v38
	v_sub_f32_e32 v38, v85, v32
	v_exp_f32_e32 v45, v38
	v_sub_f32_e32 v38, v42, v32
	v_add_f32_e32 v33, v2, v33
	v_exp_f32_e32 v49, v38
	v_sub_f32_e32 v38, v87, v32
	v_add_f32_e32 v33, v37, v33
	v_exp_f32_e32 v67, v38
	v_sub_f32_e32 v38, v86, v32
	v_add_f32_e32 v33, v41, v33
	v_exp_f32_e32 v70, v38
	v_sub_f32_e32 v38, v88, v32
	v_add_f32_e32 v33, v45, v33
	v_exp_f32_e32 v73, v38
	v_add_f32_e32 v33, v49, v33
	v_add_f32_e32 v33, v67, v33
	v_add_f32_e32 v33, v70, v33
	v_sub_f32_e32 v28, v28, v32
	v_add_f32_e32 v38, v73, v33
	v_exp_f32_e32 v33, v28
	v_sub_f32_e32 v29, v29, v32
	v_add_f32_e32 v28, v33, v38
	v_exp_f32_e32 v38, v29
	v_sub_f32_e32 v29, v30, v32
	v_exp_f32_e32 v42, v29
	v_sub_f32_e32 v29, v31, v32
	v_exp_f32_e32 v46, v29
	v_add_f32_e32 v28, v38, v28
	v_add_f32_e32 v28, v42, v28
	v_cvt_pk_bf16_f32 v30, v93, v94
	v_add_f32_e32 v28, v46, v28
	ds_bpermute_b32 v29, v64, v28
	v_add_u32_e32 v94, s8, v66
	v_add_u32_e32 v74, 0x12000, v94
	v_add_u32_e32 v76, 0x12020, v94
	v_add_u32_e32 v78, 0x14100, v94
	s_waitcnt lgkmcnt(0)
	v_add_f32_e32 v28, v28, v29
	ds_bpermute_b32 v29, v65, v28
	v_add_u32_e32 v80, 0x14120, v94
	v_add_u32_e32 v82, 0x16200, v94
	v_add_u32_e32 v84, 0x16220, v94
	v_add_u32_e32 v86, 0x18300, v94
	s_waitcnt lgkmcnt(0)
	v_add_f32_e32 v28, v28, v29
	v_sub_f32_e32 v29, v62, v32
	v_exp_f32_e32 v29, v29
	v_add_u32_e32 v88, 0x18320, v94
	ds_read_b64 v[74:75], v74
	ds_read_b64 v[76:77], v76
	ds_read_b64 v[78:79], v78
	ds_read_b64 v[80:81], v80
	v_add_f32_e32 v32, v29, v28
	v_cvt_pk_bf16_f32 v28, v89, v90
	ds_read_b64 v[82:83], v82
	ds_read_b64 v[84:85], v84
	ds_read_b64 v[86:87], v86
	ds_read_b64 v[88:89], v88
	v_cvt_pk_bf16_f32 v29, v91, v92
	v_cvt_pk_bf16_f32 v31, v95, v96
	s_add_i32 s8, s8, 32
	s_cmpk_lg_i32 s8, 0x100
	s_waitcnt lgkmcnt(6)
	v_mfma_f32_16x16x32_bf16 v[74:77], v[74:77], v[28:31], 0
	s_waitcnt lgkmcnt(4)
	v_mfma_f32_16x16x32_bf16 v[78:81], v[78:81], v[28:31], 0
	s_waitcnt lgkmcnt(2)
	v_mfma_f32_16x16x32_bf16 v[82:85], v[82:85], v[28:31], 0
	s_waitcnt lgkmcnt(0)
	v_mfma_f32_16x16x32_bf16 v[28:31], v[86:89], v[28:31], 0
	v_cvt_pk_bf16_f32 v86, v0, v34
	v_add_u32_e32 v0, 0x12040, v94
	v_add_u32_e32 v34, 0x12060, v94
	ds_read_b64 v[90:91], v0
	ds_read_b64 v[92:93], v34
	v_cvt_pk_bf16_f32 v87, v39, v43
	v_cvt_pk_bf16_f32 v88, v47, v50
	v_cvt_pk_bf16_f32 v89, v68, v71
	v_add_u32_e32 v0, 0x14140, v94
	v_add_u32_e32 v34, 0x14160, v94
	s_waitcnt lgkmcnt(0)
	v_mfma_f32_16x16x32_bf16 v[74:77], v[90:93], v[86:89], v[74:77]
	ds_read_b64 v[90:91], v0
	ds_read_b64 v[92:93], v34
	v_add_u32_e32 v0, 0x16240, v94
	v_add_u32_e32 v34, 0x16260, v94
	s_waitcnt lgkmcnt(0)
	v_mfma_f32_16x16x32_bf16 v[78:81], v[90:93], v[86:89], v[78:81]
	ds_read_b64 v[90:91], v0
	ds_read_b64 v[92:93], v34
	v_add_u32_e32 v0, 0x18340, v94
	v_add_u32_e32 v34, 0x18360, v94
	s_waitcnt lgkmcnt(0)
	v_mfma_f32_16x16x32_bf16 v[82:85], v[90:93], v[86:89], v[82:85]
	ds_read_b64 v[90:91], v0
	ds_read_b64 v[92:93], v34
	v_add_u32_e32 v0, 0x12080, v94
	s_waitcnt lgkmcnt(0)
	v_mfma_f32_16x16x32_bf16 v[28:31], v[90:93], v[86:89], v[28:31]
	v_cvt_pk_bf16_f32 v86, v1, v35
	v_add_u32_e32 v1, 0x120a0, v94
	ds_read_b64 v[90:91], v0
	ds_read_b64 v[92:93], v1
	v_cvt_pk_bf16_f32 v87, v40, v44
	v_cvt_pk_bf16_f32 v88, v48, v51
	v_cvt_pk_bf16_f32 v89, v69, v72
	v_add_u32_e32 v0, 0x14180, v94
	v_add_u32_e32 v1, 0x141a0, v94
	s_waitcnt lgkmcnt(0)
	v_mfma_f32_16x16x32_bf16 v[74:77], v[90:93], v[86:89], v[74:77]
	ds_read_b64 v[90:91], v0
	ds_read_b64 v[92:93], v1
	v_add_u32_e32 v0, 0x16280, v94
	v_add_u32_e32 v1, 0x162a0, v94
	s_waitcnt lgkmcnt(0)
	v_mfma_f32_16x16x32_bf16 v[78:81], v[90:93], v[86:89], v[78:81]
	ds_read_b64 v[90:91], v0
	ds_read_b64 v[92:93], v1
	v_add_u32_e32 v0, 0x18380, v94
	v_add_u32_e32 v1, 0x183a0, v94
	s_waitcnt lgkmcnt(0)
	v_mfma_f32_16x16x32_bf16 v[82:85], v[90:93], v[86:89], v[82:85]
	ds_read_b64 v[90:91], v0
	ds_read_b64 v[92:93], v1
	v_add_u32_e32 v0, 0x120c0, v94
	v_add_u32_e32 v1, 0x120e0, v94
	s_waitcnt lgkmcnt(0)
	v_mfma_f32_16x16x32_bf16 v[28:31], v[90:93], v[86:89], v[28:31]
	v_cvt_pk_bf16_f32 v88, v49, v67
	ds_read_b64 v[48:49], v0
	ds_read_b64 v[50:51], v1
	v_add_u32_e32 v0, 0x141c0, v94
	v_cvt_pk_bf16_f32 v89, v70, v73
	v_add_u32_e32 v1, 0x141e0, v94
	ds_read_b64 v[68:69], v0
	ds_read_b64 v[70:71], v1
	v_cvt_pk_bf16_f32 v86, v2, v37
	v_cvt_pk_bf16_f32 v87, v41, v45
	v_add_u32_e32 v0, 0x162c0, v94
	v_add_u32_e32 v1, 0x162e0, v94
	s_waitcnt lgkmcnt(2)
	v_mfma_f32_16x16x32_bf16 v[48:51], v[48:51], v[86:89], v[74:77]
	ds_read_b64 v[72:73], v0
	s_nop 1
	ds_read_b64 v[74:75], v1
	v_add_u32_e32 v0, 0x183c0, v94
	v_add_u32_e32 v1, 0x183e0, v94
	s_waitcnt lgkmcnt(2)
	v_mfma_f32_16x16x32_bf16 v[68:71], v[68:71], v[86:89], v[78:81]
	ds_read_b64 v[76:77], v0
	s_nop 1
	ds_read_b64 v[78:79], v1
	v_cvt_pk_bf16_f32 v0, v33, v38
	v_add_u32_e32 v33, 0x12100, v94
	ds_read_b64 v[38:39], v33
	v_add_u32_e32 v33, 0x14200, v94
	v_cvt_pk_bf16_f32 v1, v42, v46
	ds_read_b64 v[42:43], v33
	v_add_u32_e32 v33, 0x16300, v94
	v_mov_b32_e32 v2, v3
	ds_read_b64 v[46:47], v33
	v_add_u32_e32 v33, 0x18400, v94
	s_waitcnt lgkmcnt(1)
	v_mov_b32_e32 v44, v42
	v_mov_b32_e32 v45, v43
	v_mov_b32_e32 v40, v38
	v_mov_b32_e32 v41, v39
	v_mfma_f32_16x16x32_bf16 v[42:45], v[42:45], v[0:3], v[68:71]
	s_nop 2
	ds_read_b64 v[68:69], v33
	s_waitcnt lgkmcnt(0)
	v_mov_b32_e32 v70, v68
	v_mfma_f32_16x16x32_bf16 v[38:41], v[38:41], v[0:3], v[48:51]
	v_mov_b32_e32 v71, v69
	s_nop 1
	v_mov_b32_e32 v48, v46
	v_mov_b32_e32 v49, v47
	v_mfma_f32_16x16x32_bf16 v[72:75], v[72:75], v[86:89], v[82:85]
	v_mfma_f32_16x16x32_bf16 v[28:31], v[76:79], v[86:89], v[28:31]
	v_mfma_f32_16x16x32_bf16 v[46:49], v[46:49], v[0:3], v[72:75]
	v_mfma_f32_16x16x32_bf16 v[28:31], v[68:71], v[0:3], v[28:31]
	v_rcp_f32_e32 v0, v32
	s_nop 0
	v_pk_mul_f32 v[32:33], v[0:1], v[38:39] op_sel_hi:[0,1]
	v_pk_mul_f32 v[34:35], v[0:1], v[40:41] op_sel_hi:[0,1]
	v_cvt_pk_bf16_f32 v32, v32, v33
	v_cvt_pk_bf16_f32 v33, v34, v35
	global_store_dwordx2 v[60:61], v[32:33], off offset:-64
	v_pk_mul_f32 v[32:33], v[0:1], v[42:43] op_sel_hi:[0,1]
	v_pk_mul_f32 v[34:35], v[0:1], v[44:45] op_sel_hi:[0,1]
	v_cvt_pk_bf16_f32 v32, v32, v33
	v_cvt_pk_bf16_f32 v33, v34, v35
	global_store_dwordx2 v[60:61], v[32:33], off offset:-32
	v_pk_mul_f32 v[32:33], v[0:1], v[46:47] op_sel_hi:[0,1]
	v_pk_mul_f32 v[34:35], v[0:1], v[48:49] op_sel_hi:[0,1]
	v_pk_mul_f32 v[28:29], v[0:1], v[28:29] op_sel_hi:[0,1]
	v_pk_mul_f32 v[0:1], v[0:1], v[30:31] op_sel_hi:[0,1]
	v_cvt_pk_bf16_f32 v32, v32, v33
	v_cvt_pk_bf16_f32 v33, v34, v35
	v_cvt_pk_bf16_f32 v28, v28, v29
	v_cvt_pk_bf16_f32 v29, v0, v1
	global_store_dwordx2 v[60:61], v[32:33], off
	global_store_dwordx2 v[60:61], v[28:29], off offset:32
	v_mov_b32_e32 v0, v36
	s_waitcnt vmcnt(4)
	v_mov_b64_e32 v[34:35], v[22:23]
	v_mov_b64_e32 v[30:31], v[26:27]
	v_mov_b64_e32 v[42:43], v[18:19]
	v_mov_b64_e32 v[38:39], v[6:7]
	v_mov_b64_e32 v[50:51], v[14:15]
	v_mov_b64_e32 v[46:47], v[10:11]
	v_lshl_add_u64 v[60:61], v[60:61], 0, s[12:13]
	v_mov_b64_e32 v[32:33], v[20:21]
	v_mov_b64_e32 v[28:29], v[24:25]
	v_mov_b64_e32 v[40:41], v[16:17]
	v_mov_b64_e32 v[36:37], v[4:5]
	v_mov_b64_e32 v[48:49], v[12:13]
	v_mov_b64_e32 v[44:45], v[8:9]
	s_cbranch_scc1 .LBB0_619
	v_readlane_b32 s2, v254, 32
	s_add_i32 s29, s29, s2
	s_add_i32 s28, s28, s2
	s_cmpk_gt_i32 s29, 0xff
	s_mov_b64 s[90:91], s[18:19]
	s_cbranch_scc0 .LBB0_594
	v_readlane_b32 s4, v254, 22
	v_readlane_b32 s6, v254, 24
	v_readlane_b32 s7, v254, 25
	v_readlane_b32 s60, v254, 26
	s_mov_b64 s[66:67], s[6:7]
	v_readlane_b32 s61, v254, 27
	v_readlane_b32 s5, v254, 23
